# modp_task beside the chain: two batches of 8 weight-row loads in flight
# speedup vs baseline: 1.0189x; 1.0030x over previous
; __device__ __forceinline__ void modp_task(const Params& p, int l, int task, LAS float* sl) {
;     ...
;     f32x4 acc[5];
; #pragma unroll
;     for (int r = 0; r < 5; ++r) acc[r] = (f32x4){0.f, 0.f, 0.f, 0.f};
;     const float* wp = p.w_ada + ((size_t)l * D + k0) * 12288 + n0;
; #pragma unroll 8
;     for (int kk = 0; kk < 64; ++kk) { const f32x4 w = __builtin_nontemporal_load((const f32x4*)(wp + (size_t)kk * 12288));
; #pragma unroll
;         for (int r = 0; r < 5; ++r) acc[r] += sl[r * 64 + kk] * w; }
.LBB0_533:
	s_or_b64 exec, exec, s[2:3]
	s_mul_i32 s2, s18, 6
	s_sub_i32 s2, s9, s2
	s_lshl_b32 s2, s2, 11
	s_mul_hi_i32 s3, s19, 0xc000
	s_mul_i32 s19, s19, 0xc000
	v_lshl_add_u32 v20, v0, 2, s2
	s_add_u32 s2, s14, s19
	v_ashrrev_i32_e32 v21, 31, v20
	s_addc_u32 s3, s15, s3
	v_mov_b32_e32 v0, 0
	v_lshl_add_u64 v[22:23], v[20:21], 2, s[2:3]
	s_mov_b64 s[2:3], 0
	s_mov_b32 s19, 0
	v_mov_b32_e32 v1, v0
	v_mov_b32_e32 v2, v0
	v_mov_b32_e32 v3, v0
	v_mov_b32_e32 v16, v0
	v_mov_b32_e32 v17, v0
	v_mov_b32_e32 v18, v0
	v_mov_b32_e32 v19, v0
	v_mov_b32_e32 v12, v0
	v_mov_b32_e32 v13, v0
	v_mov_b32_e32 v14, v0
	v_mov_b32_e32 v15, v0
	v_mov_b32_e32 v8, v0
	v_mov_b32_e32 v9, v0
	v_mov_b32_e32 v10, v0
	v_mov_b32_e32 v11, v0
	v_mov_b32_e32 v4, v0
	v_mov_b32_e32 v5, v0
	v_mov_b32_e32 v6, v0
	v_mov_b32_e32 v7, v0
	s_waitcnt lgkmcnt(0)
	s_barrier
	s_mov_b32 s21, 0
	v_lshl_add_u64 v[36:37], v[22:23], 0, s[2:3]
	s_mov_b32 s20, 0x6000000
	v_lshl_add_u64 v[232:233], v[36:37], 0, s[20:21]
	global_load_dwordx4 v[170:173], v[232:233], off nt
	s_mov_b32 s20, 0x600c000
	v_lshl_add_u64 v[232:233], v[36:37], 0, s[20:21]
	global_load_dwordx4 v[174:177], v[232:233], off nt
	s_mov_b32 s20, 0x6018000
	v_lshl_add_u64 v[232:233], v[36:37], 0, s[20:21]
	global_load_dwordx4 v[178:181], v[232:233], off nt
	s_mov_b32 s20, 0x6024000
	v_lshl_add_u64 v[232:233], v[36:37], 0, s[20:21]
	global_load_dwordx4 v[182:185], v[232:233], off nt
	s_mov_b32 s20, 0x6030000
	v_lshl_add_u64 v[232:233], v[36:37], 0, s[20:21]
	global_load_dwordx4 v[186:189], v[232:233], off nt
	s_mov_b32 s20, 0x603c000
	v_lshl_add_u64 v[232:233], v[36:37], 0, s[20:21]
	global_load_dwordx4 v[190:193], v[232:233], off nt
	s_mov_b32 s20, 0x6048000
	v_lshl_add_u64 v[232:233], v[36:37], 0, s[20:21]
	global_load_dwordx4 v[204:207], v[232:233], off nt
	s_mov_b32 s20, 0x6054000
	v_lshl_add_u64 v[232:233], v[36:37], 0, s[20:21]
	global_load_dwordx4 v[208:211], v[232:233], off nt
.LBB0_534:
	v_lshl_add_u64 v[234:235], v[22:23], 0, s[2:3]
	s_mov_b32 s20, 0x60000
	v_lshl_add_u64 v[36:37], v[234:235], 0, s[20:21]
	s_mov_b32 s20, 0x6000000
	v_lshl_add_u64 v[232:233], v[36:37], 0, s[20:21]
	global_load_dwordx4 v[130:133], v[232:233], off nt
	s_mov_b32 s20, 0x600c000
	v_lshl_add_u64 v[232:233], v[36:37], 0, s[20:21]
	global_load_dwordx4 v[134:137], v[232:233], off nt
	s_mov_b32 s20, 0x6018000
	v_lshl_add_u64 v[232:233], v[36:37], 0, s[20:21]
	global_load_dwordx4 v[138:141], v[232:233], off nt
	s_mov_b32 s20, 0x6024000
	v_lshl_add_u64 v[232:233], v[36:37], 0, s[20:21]
	global_load_dwordx4 v[142:145], v[232:233], off nt
	s_mov_b32 s20, 0x6030000
	v_lshl_add_u64 v[232:233], v[36:37], 0, s[20:21]
	global_load_dwordx4 v[146:149], v[232:233], off nt
	s_mov_b32 s20, 0x603c000
	v_lshl_add_u64 v[232:233], v[36:37], 0, s[20:21]
	global_load_dwordx4 v[150:153], v[232:233], off nt
	s_mov_b32 s20, 0x6048000
	v_lshl_add_u64 v[232:233], v[36:37], 0, s[20:21]
	global_load_dwordx4 v[154:157], v[232:233], off nt
	s_mov_b32 s20, 0x6054000
	v_lshl_add_u64 v[232:233], v[36:37], 0, s[20:21]
	global_load_dwordx4 v[212:215], v[232:233], off nt
	v_mov_b32_e32 v54, s19
	ds_read_b128 v[28:31], v54
	ds_read_b128 v[32:35], v54 offset:16
	ds_read_b128 v[38:41], v54 offset:256
	ds_read_b128 v[42:45], v54 offset:272
	ds_read_b128 v[46:49], v54 offset:512
	ds_read_b128 v[50:53], v54 offset:528
	ds_read_b128 v[216:219], v54 offset:768
	ds_read_b128 v[220:223], v54 offset:784
	ds_read_b128 v[224:227], v54 offset:1024
	ds_read_b128 v[228:231], v54 offset:1040
	s_waitcnt lgkmcnt(0)
	s_waitcnt vmcnt(15)
	v_fmac_f32_e32 v16, v28, v170
	v_fmac_f32_e32 v17, v28, v171
	v_fmac_f32_e32 v18, v28, v172
	v_fmac_f32_e32 v19, v28, v173
	v_fmac_f32_e32 v12, v38, v170
	v_fmac_f32_e32 v13, v38, v171
	v_fmac_f32_e32 v14, v38, v172
	v_fmac_f32_e32 v15, v38, v173
	v_fmac_f32_e32 v8, v46, v170
	v_fmac_f32_e32 v9, v46, v171
	v_fmac_f32_e32 v10, v46, v172
	v_fmac_f32_e32 v11, v46, v173
	v_fmac_f32_e32 v4, v216, v170
	v_fmac_f32_e32 v5, v216, v171
	v_fmac_f32_e32 v6, v216, v172
	v_fmac_f32_e32 v7, v216, v173
	v_fmac_f32_e32 v0, v224, v170
	v_fmac_f32_e32 v1, v224, v171
	v_fmac_f32_e32 v2, v224, v172
	v_fmac_f32_e32 v3, v224, v173
	s_waitcnt vmcnt(14)
	v_fmac_f32_e32 v16, v29, v174
	v_fmac_f32_e32 v17, v29, v175
	v_fmac_f32_e32 v18, v29, v176
	v_fmac_f32_e32 v19, v29, v177
	v_fmac_f32_e32 v12, v39, v174
	v_fmac_f32_e32 v13, v39, v175
	v_fmac_f32_e32 v14, v39, v176
	v_fmac_f32_e32 v15, v39, v177
	v_fmac_f32_e32 v8, v47, v174
	v_fmac_f32_e32 v9, v47, v175
	v_fmac_f32_e32 v10, v47, v176
	v_fmac_f32_e32 v11, v47, v177
	v_fmac_f32_e32 v4, v217, v174
	v_fmac_f32_e32 v5, v217, v175
	v_fmac_f32_e32 v6, v217, v176
	v_fmac_f32_e32 v7, v217, v177
	v_fmac_f32_e32 v0, v225, v174
	v_fmac_f32_e32 v1, v225, v175
	v_fmac_f32_e32 v2, v225, v176
	v_fmac_f32_e32 v3, v225, v177
	s_waitcnt vmcnt(13)
	v_fmac_f32_e32 v16, v30, v178
	v_fmac_f32_e32 v17, v30, v179
	v_fmac_f32_e32 v18, v30, v180
	v_fmac_f32_e32 v19, v30, v181
	v_fmac_f32_e32 v12, v40, v178
	v_fmac_f32_e32 v13, v40, v179
	v_fmac_f32_e32 v14, v40, v180
	v_fmac_f32_e32 v15, v40, v181
	v_fmac_f32_e32 v8, v48, v178
	v_fmac_f32_e32 v9, v48, v179
	v_fmac_f32_e32 v10, v48, v180
	v_fmac_f32_e32 v11, v48, v181
	v_fmac_f32_e32 v4, v218, v178
	v_fmac_f32_e32 v5, v218, v179
	v_fmac_f32_e32 v6, v218, v180
	v_fmac_f32_e32 v7, v218, v181
	v_fmac_f32_e32 v0, v226, v178
	v_fmac_f32_e32 v1, v226, v179
	v_fmac_f32_e32 v2, v226, v180
	v_fmac_f32_e32 v3, v226, v181
	s_waitcnt vmcnt(12)
; __device__ __forceinline__ void modp_task(const Params& p, int l, int task, LAS float* sl) {
;     ...
; #pragma unroll 8
;     for (int kk = 0; kk < 64; ++kk) { const f32x4 w = __builtin_nontemporal_load((const f32x4*)(wp + (size_t)kk * 12288));
; #pragma unroll
;         for (int r = 0; r < 5; ++r) acc[r] += sl[r * 64 + kk] * w; }
	v_fmac_f32_e32 v16, v31, v182
	v_fmac_f32_e32 v17, v31, v183
	v_fmac_f32_e32 v18, v31, v184
	v_fmac_f32_e32 v19, v31, v185
	v_fmac_f32_e32 v12, v41, v182
	v_fmac_f32_e32 v13, v41, v183
	v_fmac_f32_e32 v14, v41, v184
	v_fmac_f32_e32 v15, v41, v185
	v_fmac_f32_e32 v8, v49, v182
	v_fmac_f32_e32 v9, v49, v183
	v_fmac_f32_e32 v10, v49, v184
	v_fmac_f32_e32 v11, v49, v185
	v_fmac_f32_e32 v4, v219, v182
	v_fmac_f32_e32 v5, v219, v183
	v_fmac_f32_e32 v6, v219, v184
	v_fmac_f32_e32 v7, v219, v185
	v_fmac_f32_e32 v0, v227, v182
	v_fmac_f32_e32 v1, v227, v183
	v_fmac_f32_e32 v2, v227, v184
	v_fmac_f32_e32 v3, v227, v185
	s_waitcnt vmcnt(11)
	v_fmac_f32_e32 v16, v32, v186
	v_fmac_f32_e32 v17, v32, v187
	v_fmac_f32_e32 v18, v32, v188
	v_fmac_f32_e32 v19, v32, v189
	v_fmac_f32_e32 v12, v42, v186
	v_fmac_f32_e32 v13, v42, v187
	v_fmac_f32_e32 v14, v42, v188
	v_fmac_f32_e32 v15, v42, v189
	v_fmac_f32_e32 v8, v50, v186
	v_fmac_f32_e32 v9, v50, v187
	v_fmac_f32_e32 v10, v50, v188
	v_fmac_f32_e32 v11, v50, v189
	v_fmac_f32_e32 v4, v220, v186
	v_fmac_f32_e32 v5, v220, v187
	v_fmac_f32_e32 v6, v220, v188
	v_fmac_f32_e32 v7, v220, v189
	v_fmac_f32_e32 v0, v228, v186
	v_fmac_f32_e32 v1, v228, v187
	v_fmac_f32_e32 v2, v228, v188
	v_fmac_f32_e32 v3, v228, v189
	s_waitcnt vmcnt(10)
	v_fmac_f32_e32 v16, v33, v190
	v_fmac_f32_e32 v17, v33, v191
	v_fmac_f32_e32 v18, v33, v192
	v_fmac_f32_e32 v19, v33, v193
	v_fmac_f32_e32 v12, v43, v190
	v_fmac_f32_e32 v13, v43, v191
	v_fmac_f32_e32 v14, v43, v192
	v_fmac_f32_e32 v15, v43, v193
	v_fmac_f32_e32 v8, v51, v190
	v_fmac_f32_e32 v9, v51, v191
	v_fmac_f32_e32 v10, v51, v192
	v_fmac_f32_e32 v11, v51, v193
	v_fmac_f32_e32 v4, v221, v190
	v_fmac_f32_e32 v5, v221, v191
	v_fmac_f32_e32 v6, v221, v192
	v_fmac_f32_e32 v7, v221, v193
	v_fmac_f32_e32 v0, v229, v190
	v_fmac_f32_e32 v1, v229, v191
	v_fmac_f32_e32 v2, v229, v192
	v_fmac_f32_e32 v3, v229, v193
	s_waitcnt vmcnt(9)
	v_fmac_f32_e32 v16, v34, v204
	v_fmac_f32_e32 v17, v34, v205
	v_fmac_f32_e32 v18, v34, v206
	v_fmac_f32_e32 v19, v34, v207
	v_fmac_f32_e32 v12, v44, v204
	v_fmac_f32_e32 v13, v44, v205
	v_fmac_f32_e32 v14, v44, v206
	v_fmac_f32_e32 v15, v44, v207
	v_fmac_f32_e32 v8, v52, v204
	v_fmac_f32_e32 v9, v52, v205
	v_fmac_f32_e32 v10, v52, v206
	v_fmac_f32_e32 v11, v52, v207
	v_fmac_f32_e32 v4, v222, v204
	v_fmac_f32_e32 v5, v222, v205
	v_fmac_f32_e32 v6, v222, v206
	v_fmac_f32_e32 v7, v222, v207
	v_fmac_f32_e32 v0, v230, v204
	v_fmac_f32_e32 v1, v230, v205
	v_fmac_f32_e32 v2, v230, v206
	v_fmac_f32_e32 v3, v230, v207
	s_waitcnt vmcnt(8)
	v_fmac_f32_e32 v16, v35, v208
	v_fmac_f32_e32 v17, v35, v209
	v_fmac_f32_e32 v18, v35, v210
	v_fmac_f32_e32 v19, v35, v211
	v_fmac_f32_e32 v12, v45, v208
	v_fmac_f32_e32 v13, v45, v209
	v_fmac_f32_e32 v14, v45, v210
	v_fmac_f32_e32 v15, v45, v211
	v_fmac_f32_e32 v8, v53, v208
	v_fmac_f32_e32 v9, v53, v209
	v_fmac_f32_e32 v10, v53, v210
	v_fmac_f32_e32 v11, v53, v211
	v_fmac_f32_e32 v4, v223, v208
	v_fmac_f32_e32 v5, v223, v209
	v_fmac_f32_e32 v6, v223, v210
	v_fmac_f32_e32 v7, v223, v211
	v_fmac_f32_e32 v0, v231, v208
	v_fmac_f32_e32 v1, v231, v209
	v_fmac_f32_e32 v2, v231, v210
	v_fmac_f32_e32 v3, v231, v211
	s_add_u32 s20, s2, 0xc0000
	s_min_u32 s20, s20, 0x2a0000
	s_sub_u32 s20, s20, s2
	v_lshl_add_u64 v[36:37], v[234:235], 0, s[20:21]
	s_mov_b32 s20, 0x6000000
	v_lshl_add_u64 v[232:233], v[36:37], 0, s[20:21]
	global_load_dwordx4 v[170:173], v[232:233], off nt
	s_mov_b32 s20, 0x600c000
	v_lshl_add_u64 v[232:233], v[36:37], 0, s[20:21]
	global_load_dwordx4 v[174:177], v[232:233], off nt
	s_mov_b32 s20, 0x6018000
	v_lshl_add_u64 v[232:233], v[36:37], 0, s[20:21]
	global_load_dwordx4 v[178:181], v[232:233], off nt
	s_mov_b32 s20, 0x6024000
	v_lshl_add_u64 v[232:233], v[36:37], 0, s[20:21]
	global_load_dwordx4 v[182:185], v[232:233], off nt
	s_mov_b32 s20, 0x6030000
	v_lshl_add_u64 v[232:233], v[36:37], 0, s[20:21]
	global_load_dwordx4 v[186:189], v[232:233], off nt
	s_mov_b32 s20, 0x603c000
	v_lshl_add_u64 v[232:233], v[36:37], 0, s[20:21]
	global_load_dwordx4 v[190:193], v[232:233], off nt
	s_mov_b32 s20, 0x6048000
	v_lshl_add_u64 v[232:233], v[36:37], 0, s[20:21]
	global_load_dwordx4 v[204:207], v[232:233], off nt
	s_mov_b32 s20, 0x6054000
	v_lshl_add_u64 v[232:233], v[36:37], 0, s[20:21]
	global_load_dwordx4 v[208:211], v[232:233], off nt
	s_add_i32 s19, s19, 32
	v_mov_b32_e32 v54, s19
	ds_read_b128 v[28:31], v54
	ds_read_b128 v[32:35], v54 offset:16
	ds_read_b128 v[38:41], v54 offset:256
	ds_read_b128 v[42:45], v54 offset:272
	ds_read_b128 v[46:49], v54 offset:512
	ds_read_b128 v[50:53], v54 offset:528
	ds_read_b128 v[216:219], v54 offset:768
	ds_read_b128 v[220:223], v54 offset:784
	ds_read_b128 v[224:227], v54 offset:1024
	ds_read_b128 v[228:231], v54 offset:1040
	s_waitcnt lgkmcnt(0)
	s_waitcnt vmcnt(15)
	v_fmac_f32_e32 v16, v28, v130
	v_fmac_f32_e32 v17, v28, v131
	v_fmac_f32_e32 v18, v28, v132
	v_fmac_f32_e32 v19, v28, v133
	v_fmac_f32_e32 v12, v38, v130
	v_fmac_f32_e32 v13, v38, v131
	v_fmac_f32_e32 v14, v38, v132
	v_fmac_f32_e32 v15, v38, v133
	v_fmac_f32_e32 v8, v46, v130
	v_fmac_f32_e32 v9, v46, v131
	v_fmac_f32_e32 v10, v46, v132
	v_fmac_f32_e32 v11, v46, v133
	v_fmac_f32_e32 v4, v216, v130
	v_fmac_f32_e32 v5, v216, v131
	v_fmac_f32_e32 v6, v216, v132
	v_fmac_f32_e32 v7, v216, v133
	v_fmac_f32_e32 v0, v224, v130
	v_fmac_f32_e32 v1, v224, v131
	v_fmac_f32_e32 v2, v224, v132
	v_fmac_f32_e32 v3, v224, v133
	s_waitcnt vmcnt(14)
; __device__ __forceinline__ void modp_task(const Params& p, int l, int task, LAS float* sl) {
;     ...
; #pragma unroll 8
;     for (int kk = 0; kk < 64; ++kk) { const f32x4 w = __builtin_nontemporal_load((const f32x4*)(wp + (size_t)kk * 12288));
; #pragma unroll
;         for (int r = 0; r < 5; ++r) acc[r] += sl[r * 64 + kk] * w; }
;     float* mp = (float*)(p.ws + OFF_MODP) + ((size_t)(s * 2 + l) * 5) * 12288 + n0;
; #pragma unroll
;     for (int r = 0; r < 5; ++r) *(f32x4*)(mp + (size_t)r * 12288) = acc[r];
;     __syncthreads();
	v_fmac_f32_e32 v16, v29, v134
	v_fmac_f32_e32 v17, v29, v135
	v_fmac_f32_e32 v18, v29, v136
	v_fmac_f32_e32 v19, v29, v137
	v_fmac_f32_e32 v12, v39, v134
	v_fmac_f32_e32 v13, v39, v135
	v_fmac_f32_e32 v14, v39, v136
	v_fmac_f32_e32 v15, v39, v137
	v_fmac_f32_e32 v8, v47, v134
	v_fmac_f32_e32 v9, v47, v135
	v_fmac_f32_e32 v10, v47, v136
	v_fmac_f32_e32 v11, v47, v137
	v_fmac_f32_e32 v4, v217, v134
	v_fmac_f32_e32 v5, v217, v135
	v_fmac_f32_e32 v6, v217, v136
	v_fmac_f32_e32 v7, v217, v137
	v_fmac_f32_e32 v0, v225, v134
	v_fmac_f32_e32 v1, v225, v135
	v_fmac_f32_e32 v2, v225, v136
	v_fmac_f32_e32 v3, v225, v137
	s_waitcnt vmcnt(13)
	v_fmac_f32_e32 v16, v30, v138
	v_fmac_f32_e32 v17, v30, v139
	v_fmac_f32_e32 v18, v30, v140
	v_fmac_f32_e32 v19, v30, v141
	v_fmac_f32_e32 v12, v40, v138
	v_fmac_f32_e32 v13, v40, v139
	v_fmac_f32_e32 v14, v40, v140
	v_fmac_f32_e32 v15, v40, v141
	v_fmac_f32_e32 v8, v48, v138
	v_fmac_f32_e32 v9, v48, v139
	v_fmac_f32_e32 v10, v48, v140
	v_fmac_f32_e32 v11, v48, v141
	v_fmac_f32_e32 v4, v218, v138
	v_fmac_f32_e32 v5, v218, v139
	v_fmac_f32_e32 v6, v218, v140
	v_fmac_f32_e32 v7, v218, v141
	v_fmac_f32_e32 v0, v226, v138
	v_fmac_f32_e32 v1, v226, v139
	v_fmac_f32_e32 v2, v226, v140
	v_fmac_f32_e32 v3, v226, v141
	s_waitcnt vmcnt(12)
	v_fmac_f32_e32 v16, v31, v142
	v_fmac_f32_e32 v17, v31, v143
	v_fmac_f32_e32 v18, v31, v144
	v_fmac_f32_e32 v19, v31, v145
	v_fmac_f32_e32 v12, v41, v142
	v_fmac_f32_e32 v13, v41, v143
	v_fmac_f32_e32 v14, v41, v144
	v_fmac_f32_e32 v15, v41, v145
	v_fmac_f32_e32 v8, v49, v142
	v_fmac_f32_e32 v9, v49, v143
	v_fmac_f32_e32 v10, v49, v144
	v_fmac_f32_e32 v11, v49, v145
	v_fmac_f32_e32 v4, v219, v142
	v_fmac_f32_e32 v5, v219, v143
	v_fmac_f32_e32 v6, v219, v144
	v_fmac_f32_e32 v7, v219, v145
	v_fmac_f32_e32 v0, v227, v142
	v_fmac_f32_e32 v1, v227, v143
	v_fmac_f32_e32 v2, v227, v144
	v_fmac_f32_e32 v3, v227, v145
	s_waitcnt vmcnt(11)
	v_fmac_f32_e32 v16, v32, v146
	v_fmac_f32_e32 v17, v32, v147
	v_fmac_f32_e32 v18, v32, v148
	v_fmac_f32_e32 v19, v32, v149
	v_fmac_f32_e32 v12, v42, v146
	v_fmac_f32_e32 v13, v42, v147
	v_fmac_f32_e32 v14, v42, v148
	v_fmac_f32_e32 v15, v42, v149
	v_fmac_f32_e32 v8, v50, v146
	v_fmac_f32_e32 v9, v50, v147
	v_fmac_f32_e32 v10, v50, v148
	v_fmac_f32_e32 v11, v50, v149
	v_fmac_f32_e32 v4, v220, v146
	v_fmac_f32_e32 v5, v220, v147
	v_fmac_f32_e32 v6, v220, v148
	v_fmac_f32_e32 v7, v220, v149
	v_fmac_f32_e32 v0, v228, v146
	v_fmac_f32_e32 v1, v228, v147
	v_fmac_f32_e32 v2, v228, v148
	v_fmac_f32_e32 v3, v228, v149
	s_waitcnt vmcnt(10)
	v_fmac_f32_e32 v16, v33, v150
	v_fmac_f32_e32 v17, v33, v151
	v_fmac_f32_e32 v18, v33, v152
	v_fmac_f32_e32 v19, v33, v153
	v_fmac_f32_e32 v12, v43, v150
	v_fmac_f32_e32 v13, v43, v151
	v_fmac_f32_e32 v14, v43, v152
	v_fmac_f32_e32 v15, v43, v153
	v_fmac_f32_e32 v8, v51, v150
	v_fmac_f32_e32 v9, v51, v151
	v_fmac_f32_e32 v10, v51, v152
	v_fmac_f32_e32 v11, v51, v153
	v_fmac_f32_e32 v4, v221, v150
	v_fmac_f32_e32 v5, v221, v151
	v_fmac_f32_e32 v6, v221, v152
	v_fmac_f32_e32 v7, v221, v153
	v_fmac_f32_e32 v0, v229, v150
	v_fmac_f32_e32 v1, v229, v151
	v_fmac_f32_e32 v2, v229, v152
	v_fmac_f32_e32 v3, v229, v153
	s_waitcnt vmcnt(9)
	v_fmac_f32_e32 v16, v34, v154
	v_fmac_f32_e32 v17, v34, v155
	v_fmac_f32_e32 v18, v34, v156
	v_fmac_f32_e32 v19, v34, v157
	v_fmac_f32_e32 v12, v44, v154
	v_fmac_f32_e32 v13, v44, v155
	v_fmac_f32_e32 v14, v44, v156
	v_fmac_f32_e32 v15, v44, v157
	v_fmac_f32_e32 v8, v52, v154
	v_fmac_f32_e32 v9, v52, v155
	v_fmac_f32_e32 v10, v52, v156
	v_fmac_f32_e32 v11, v52, v157
	v_fmac_f32_e32 v4, v222, v154
	v_fmac_f32_e32 v5, v222, v155
	v_fmac_f32_e32 v6, v222, v156
	v_fmac_f32_e32 v7, v222, v157
	v_fmac_f32_e32 v0, v230, v154
	v_fmac_f32_e32 v1, v230, v155
	v_fmac_f32_e32 v2, v230, v156
	v_fmac_f32_e32 v3, v230, v157
	s_waitcnt vmcnt(8)
	v_fmac_f32_e32 v16, v35, v212
	v_fmac_f32_e32 v17, v35, v213
	v_fmac_f32_e32 v18, v35, v214
	v_fmac_f32_e32 v19, v35, v215
	v_fmac_f32_e32 v12, v45, v212
	v_fmac_f32_e32 v13, v45, v213
	v_fmac_f32_e32 v14, v45, v214
	v_fmac_f32_e32 v15, v45, v215
	v_fmac_f32_e32 v8, v53, v212
	v_fmac_f32_e32 v9, v53, v213
	v_fmac_f32_e32 v10, v53, v214
	v_fmac_f32_e32 v11, v53, v215
	v_fmac_f32_e32 v4, v223, v212
	v_fmac_f32_e32 v5, v223, v213
	v_fmac_f32_e32 v6, v223, v214
	v_fmac_f32_e32 v7, v223, v215
	v_fmac_f32_e32 v0, v231, v212
	v_fmac_f32_e32 v1, v231, v213
	v_fmac_f32_e32 v2, v231, v214
	v_fmac_f32_e32 v3, v231, v215
	s_add_u32 s2, s2, 0xc0000
	s_addc_u32 s3, s3, 0
	s_add_i32 s19, s19, 32
	s_cmp_lg_u32 s2, 0x300000
	s_cbranch_scc1 .LBB0_534
	s_waitcnt vmcnt(0)
	s_lshl_b32 s2, s18, 1
	s_or_b32 s2, s2, 1
	s_mul_hi_i32 s3, s2, 0x3c000
	s_mul_i32 s2, s2, 0x3c000
	s_add_u32 s2, s1, s2
	s_addc_u32 s3, s8, s3
	v_lshl_add_u64 v[20:21], v[20:21], 2, s[2:3]
	s_mov_b32 s2, 0xc000
	global_store_dwordx4 v[20:21], v[16:19], off
	s_nop 1
	v_add_co_u32_e32 v16, vcc, s2, v20
	s_mov_b32 s2, 0x18000
	s_nop 0
	v_addc_co_u32_e32 v17, vcc, 0, v21, vcc
	global_store_dwordx4 v[16:17], v[12:15], off
	s_nop 1
	v_add_co_u32_e32 v12, vcc, s2, v20
	v_readlane_b32 s2, v239, 43
	s_nop 0
	v_addc_co_u32_e32 v13, vcc, 0, v21, vcc
	global_store_dwordx4 v[12:13], v[8:11], off
	s_add_i32 s9, s2, s9
	s_cmpk_lt_i32 s9, 0xc0
	v_add_co_u32_e32 v8, vcc, 0x24000, v20
	s_nop 1
	v_addc_co_u32_e32 v9, vcc, 0, v21, vcc
	global_store_dwordx4 v[8:9], v[4:7], off
	s_nop 1
	v_add_co_u32_e32 v4, vcc, 0x30000, v20
	s_nop 1
	v_addc_co_u32_e32 v5, vcc, 0, v21, vcc
	global_store_dwordx4 v[4:5], v[0:3], off
	s_barrier
	s_cbranch_scc1 .LBB0_531
